# LayerNorm row loop: next row's loads prefetched into a second register set while the current row is reduced, normalised and stored
# speedup vs baseline: 1.0039x; 1.0039x over previous
; __device__ __forceinline__ float wave_sum(float v) {
; #pragma unroll
;     for (int o = 1; o < 64; o <<= 1) v += __shfl_xor(v, o);
;     return v;
.LBB0_186:
	s_cmp_lt_i32 s14, 1
	s_cbranch_scc1 .LBB0_193
	v_and_b32_e32 v67, 64, v217
	v_add_u32_e32 v67, 64, v67
	v_xor_b32_e32 v68, 1, v217
	v_cmp_lt_i32_e32 vcc, v68, v67
	v_readlane_b32 s4, v253, 34
	v_lshlrev_b32_e32 v98, 4, v66
	v_cndmask_b32_e32 v68, v217, v68, vcc
	v_lshlrev_b32_e32 v104, 2, v68
	v_xor_b32_e32 v68, 2, v217
	v_cmp_lt_i32_e32 vcc, v68, v67
	v_readlane_b32 s5, v253, 35
	v_lshl_add_u64 v[82:83], s[88:89], 0, v[98:99]
	v_cndmask_b32_e32 v68, v217, v68, vcc
	v_lshlrev_b32_e32 v105, 2, v68
	v_xor_b32_e32 v68, 4, v217
	v_cmp_lt_i32_e32 vcc, v68, v67
	s_mov_b32 s15, 0
	v_cmp_eq_u32_e64 s[0:1], 0, v66
	v_cndmask_b32_e32 v68, v217, v68, vcc
	v_lshlrev_b32_e32 v106, 2, v68
	v_xor_b32_e32 v68, 8, v217
	v_cmp_lt_i32_e32 vcc, v68, v67
	v_lshl_add_u64 v[84:85], s[4:5], 0, v[98:99]
	s_mov_b32 s16, s14
	v_cndmask_b32_e32 v68, v217, v68, vcc
	v_lshlrev_b32_e32 v107, 2, v68
	v_xor_b32_e32 v68, 16, v217
	v_cmp_lt_i32_e32 vcc, v68, v67
	v_readlane_b32 s17, v249, 41
	s_nop 0
	v_cndmask_b32_e32 v68, v217, v68, vcc
	v_lshlrev_b32_e32 v108, 2, v68
	v_xor_b32_e32 v68, 32, v217
	v_cmp_lt_i32_e32 vcc, v68, v67
	s_nop 1
	v_cndmask_b32_e32 v67, v217, v68, vcc
	v_lshlrev_b32_e32 v109, 2, v67
	s_not_b32 s100, s15
	s_add_i32 s100, s14, s100
	s_mul_i32 s100, s100, s64
	s_add_i32 s100, s100, s79
	s_and_b64 vcc, exec, s[8:9]
	s_cselect_b32 s100, s100, s17
	s_ashr_i32 s101, s100, 31
	s_lshl_b64 s[100:101], s[100:101], 12
	v_lshl_add_u64 v[170:171], v[82:83], 0, s[100:101]
	global_load_dwordx4 v[154:157], v[170:171], off
	global_load_dwordx4 v[158:161], v[170:171], off offset:1024
	global_load_dwordx4 v[162:165], v[170:171], off offset:2048
	global_load_dwordx4 v[166:169], v[170:171], off offset:3072
	s_branch .LBB0_189

.LBB0_191:
	s_ashr_i32 s13, s12, 31
	s_lshl_b64 s[4:5], s[12:13], 12
	v_lshl_add_u64 v[66:67], v[82:83], 0, s[4:5]
	s_sub_i32 s100, s12, s64
	s_add_i32 s101, s17, s43
	s_and_b64 vcc, exec, s[8:9]
	s_cselect_b32 s100, s100, s101
	s_ashr_i32 s101, s100, 31
	s_lshl_b64 s[100:101], s[100:101], 12
	v_lshl_add_u64 v[170:171], v[82:83], 0, s[100:101]
	s_cmp_lg_u32 s15, 0
	s_cbranch_scc1 .Lln_wA
	s_waitcnt vmcnt(0)
.Lln_wA:
	v_mov_b32_e32 v102, v99
	s_waitcnt vmcnt(8)
	v_mov_b64_e32 v[78:79], v[154:155]
	v_mov_b64_e32 v[80:81], v[156:157]
	v_cvt_f32_f16_sdwa v73, v80 dst_sel:DWORD dst_unused:UNUSED_PAD src0_sel:WORD_1
	v_cvt_f32_f16_sdwa v72, v78 dst_sel:DWORD dst_unused:UNUSED_PAD src0_sel:WORD_1
	v_cvt_f32_f16_e32 v75, v80
	v_cvt_f32_f16_e32 v74, v78
	v_cvt_f32_f16_sdwa v69, v81 dst_sel:DWORD dst_unused:UNUSED_PAD src0_sel:WORD_1
	v_cvt_f32_f16_sdwa v68, v79 dst_sel:DWORD dst_unused:UNUSED_PAD src0_sel:WORD_1
	v_cvt_f32_f16_e32 v71, v81
	v_pk_add_f32 v[72:73], v[74:75], v[72:73]
	v_cvt_f32_f16_e32 v70, v79
	v_pk_add_f32 v[68:69], v[70:71], v[68:69]
	s_nop 0
	v_pk_add_f32 v[68:69], v[72:73], v[68:69]
	s_waitcnt vmcnt(7)
	v_mov_b64_e32 v[74:75], v[158:159]
	v_mov_b64_e32 v[76:77], v[160:161]
	v_cvt_f32_f16_e32 v72, v74
	v_cvt_f32_f16_sdwa v73, v75 dst_sel:DWORD dst_unused:UNUSED_PAD src0_sel:WORD_1
	v_cvt_f32_f16_e32 v87, v75
	v_cvt_f32_f16_sdwa v86, v74 dst_sel:DWORD dst_unused:UNUSED_PAD src0_sel:WORD_1
	v_pk_add_f32 v[94:95], v[68:69], v[68:69] op_sel:[0,1] op_sel_hi:[1,0]
	v_cvt_f32_f16_e32 v68, v76
	v_cvt_f32_f16_sdwa v69, v77 dst_sel:DWORD dst_unused:UNUSED_PAD src0_sel:WORD_1
	v_cvt_f32_f16_e32 v71, v77
	v_cvt_f32_f16_sdwa v70, v76 dst_sel:DWORD dst_unused:UNUSED_PAD src0_sel:WORD_1
	v_pk_add_f32 v[72:73], v[86:87], v[72:73]
	v_pk_add_f32 v[68:69], v[70:71], v[68:69]
	v_pk_add_f32 v[96:97], v[72:73], v[72:73] op_sel:[0,1] op_sel_hi:[1,0]
	v_pk_add_f32 v[100:101], v[68:69], v[68:69] op_sel:[0,1] op_sel_hi:[1,0]
	s_waitcnt vmcnt(6)
	v_mov_b64_e32 v[70:71], v[162:163]
	v_mov_b64_e32 v[72:73], v[164:165]
	v_cvt_f32_f16_e32 v68, v73
	v_cvt_f32_f16_sdwa v69, v73 dst_sel:DWORD dst_unused:UNUSED_PAD src0_sel:WORD_1
	v_cvt_f32_f16_e32 v88, v71
	v_cvt_f32_f16_sdwa v89, v71 dst_sel:DWORD dst_unused:UNUSED_PAD src0_sel:WORD_1
	v_cvt_f32_f16_e32 v86, v72
	v_cvt_f32_f16_sdwa v87, v72 dst_sel:DWORD dst_unused:UNUSED_PAD src0_sel:WORD_1
	v_cvt_f32_f16_e32 v90, v70
	v_add_f32_e32 v92, v88, v89
	v_add_f32_e32 v88, v68, v69
	v_cvt_f32_f16_sdwa v91, v70 dst_sel:DWORD dst_unused:UNUSED_PAD src0_sel:WORD_1
	v_add_f32_e32 v86, v86, v87
	v_add_f32_e32 v90, v90, v91
	s_waitcnt vmcnt(5)
	v_mov_b64_e32 v[66:67], v[166:167]
	v_mov_b64_e32 v[68:69], v[168:169]
	s_cmp_eq_u32 s16, 1
	s_cbranch_scc1 .Lln_npA
	global_load_dwordx4 v[154:157], v[170:171], off
	global_load_dwordx4 v[158:161], v[170:171], off offset:1024
	global_load_dwordx4 v[162:165], v[170:171], off offset:2048
	global_load_dwordx4 v[166:169], v[170:171], off offset:3072
.Lln_npA:
	v_cvt_f32_f16_sdwa v89, v69 dst_sel:DWORD dst_unused:UNUSED_PAD src0_sel:WORD_1
	v_cvt_f32_f16_e32 v87, v69
	v_cvt_f32_f16_sdwa v93, v68 dst_sel:DWORD dst_unused:UNUSED_PAD src0_sel:WORD_1
	v_cvt_f32_f16_e32 v91, v68
	v_cvt_f32_f16_e32 v97, v67
	v_cvt_f32_f16_sdwa v101, v67 dst_sel:DWORD dst_unused:UNUSED_PAD src0_sel:WORD_1
	v_cvt_f32_f16_e32 v95, v66
	v_cvt_f32_f16_sdwa v103, v66 dst_sel:DWORD dst_unused:UNUSED_PAD src0_sel:WORD_1
	v_pk_add_f32 v[90:91], v[90:91], v[92:93]
	v_pk_add_f32 v[96:97], v[96:97], v[100:101]
	v_pk_add_f32 v[86:87], v[86:87], v[88:89]
	v_pk_add_f32 v[94:95], v[94:95], v[102:103]
	v_pk_add_f32 v[86:87], v[90:91], v[86:87]
	v_pk_add_f32 v[94:95], v[94:95], v[96:97]
	s_nop 0
	v_pk_add_f32 v[86:87], v[94:95], v[86:87]
	s_nop 0
	v_add_f32_e32 v86, v86, v87
	ds_bpermute_b32 v87, v104, v86
	s_waitcnt lgkmcnt(0)
	v_add_f32_e32 v86, v86, v87
	ds_bpermute_b32 v87, v105, v86
	s_waitcnt lgkmcnt(0)
	v_add_f32_e32 v86, v86, v87
	ds_bpermute_b32 v87, v106, v86
	s_waitcnt lgkmcnt(0)
	v_add_f32_e32 v86, v86, v87
	ds_bpermute_b32 v87, v107, v86
	s_waitcnt lgkmcnt(0)
	v_add_f32_e32 v86, v86, v87
	ds_bpermute_b32 v87, v108, v86
	s_waitcnt lgkmcnt(0)
	v_add_f32_e32 v86, v86, v87
	ds_bpermute_b32 v87, v109, v86
	s_waitcnt lgkmcnt(0)
	v_add_f32_e32 v110, v86, v87
	v_fma_mix_f32 v87, v110, s80, v81 op_sel:[0,0,1] op_sel_hi:[0,0,1]
	v_fma_mix_f32 v86, v110, s80, v81 op_sel_hi:[0,0,1]
	v_fma_mix_f32 v81, v110, s80, v80 op_sel:[0,0,1] op_sel_hi:[0,0,1]
	v_fma_mix_f32 v80, v110, s80, v80 op_sel_hi:[0,0,1]
	v_fma_mix_f32 v89, v110, s80, v79 op_sel:[0,0,1] op_sel_hi:[0,0,1]
	v_fma_mix_f32 v88, v110, s80, v79 op_sel_hi:[0,0,1]
	v_fma_mix_f32 v79, v110, s80, v78 op_sel:[0,0,1] op_sel_hi:[0,0,1]
	v_fma_mix_f32 v78, v110, s80, v78 op_sel_hi:[0,0,1]
	v_pk_mul_f32 v[90:91], v[86:87], v[86:87]
	v_pk_mul_f32 v[92:93], v[80:81], v[80:81]
	v_pk_mul_f32 v[94:95], v[88:89], v[88:89]
	v_pk_mul_f32 v[96:97], v[78:79], v[78:79]
	v_add_f32_e32 v94, v94, v95
	v_add_f32_e32 v96, v96, v97
	v_add_f32_e32 v92, v92, v93
	v_add_f32_e32 v90, v90, v91
	v_add_f32_e32 v94, v96, v94
	v_add_f32_e32 v90, v92, v90
	v_add_f32_e32 v98, v94, v90
	v_fma_mix_f32 v91, v110, s80, v77 op_sel:[0,0,1] op_sel_hi:[0,0,1]
	v_fma_mix_f32 v90, v110, s80, v77 op_sel_hi:[0,0,1]
	v_fma_mix_f32 v77, v110, s80, v76 op_sel:[0,0,1] op_sel_hi:[0,0,1]
	v_fma_mix_f32 v76, v110, s80, v76 op_sel_hi:[0,0,1]
	v_fma_mix_f32 v93, v110, s80, v75 op_sel:[0,0,1] op_sel_hi:[0,0,1]
	v_fma_mix_f32 v92, v110, s80, v75 op_sel_hi:[0,0,1]
	v_fma_mix_f32 v75, v110, s80, v74 op_sel:[0,0,1] op_sel_hi:[0,0,1]
	v_fma_mix_f32 v74, v110, s80, v74 op_sel_hi:[0,0,1]
	v_pk_mul_f32 v[94:95], v[90:91], v[90:91]
	v_pk_mul_f32 v[96:97], v[76:77], v[76:77]
	v_pk_mul_f32 v[100:101], v[92:93], v[92:93]
	v_pk_mul_f32 v[102:103], v[74:75], v[74:75]
	v_add_f32_e32 v100, v100, v101
	v_add_f32_e32 v102, v102, v103
	v_add_f32_e32 v96, v96, v97
	v_add_f32_e32 v94, v94, v95
	v_add_f32_e32 v100, v102, v100
	v_add_f32_e32 v94, v96, v94
	v_add_f32_e32 v94, v100, v94
	v_add_f32_e32 v98, v98, v94
	v_fma_mix_f32 v95, v110, s80, v73 op_sel:[0,0,1] op_sel_hi:[0,0,1]
	v_fma_mix_f32 v94, v110, s80, v73 op_sel_hi:[0,0,1]
	v_fma_mix_f32 v73, v110, s80, v72 op_sel:[0,0,1] op_sel_hi:[0,0,1]
	v_fma_mix_f32 v72, v110, s80, v72 op_sel_hi:[0,0,1]
	v_fma_mix_f32 v97, v110, s80, v71 op_sel:[0,0,1] op_sel_hi:[0,0,1]
	v_fma_mix_f32 v96, v110, s80, v71 op_sel_hi:[0,0,1]
	v_fma_mix_f32 v71, v110, s80, v70 op_sel:[0,0,1] op_sel_hi:[0,0,1]
	v_fma_mix_f32 v70, v110, s80, v70 op_sel_hi:[0,0,1]
	v_pk_mul_f32 v[100:101], v[94:95], v[94:95]
	v_pk_mul_f32 v[102:103], v[72:73], v[72:73]
	v_pk_mul_f32 v[112:113], v[96:97], v[96:97]
	v_pk_mul_f32 v[114:115], v[70:71], v[70:71]
	v_add_f32_e32 v112, v112, v113
	v_add_f32_e32 v111, v114, v115
	v_add_f32_e32 v102, v102, v103
	v_add_f32_e32 v100, v100, v101
	v_add_f32_e32 v111, v111, v112
	v_add_f32_e32 v100, v102, v100
	v_add_f32_e32 v100, v111, v100
	v_add_f32_e32 v98, v98, v100
	v_fma_mix_f32 v101, v110, s80, v69 op_sel:[0,0,1] op_sel_hi:[0,0,1]
	v_fma_mix_f32 v100, v110, s80, v69 op_sel_hi:[0,0,1]
	v_fma_mix_f32 v69, v110, s80, v68 op_sel:[0,0,1] op_sel_hi:[0,0,1]
	v_fma_mix_f32 v68, v110, s80, v68 op_sel_hi:[0,0,1]
	v_fma_mix_f32 v103, v110, s80, v67 op_sel:[0,0,1] op_sel_hi:[0,0,1]
	v_fma_mix_f32 v102, v110, s80, v67 op_sel_hi:[0,0,1]
	v_fma_mix_f32 v67, v110, s80, v66 op_sel:[0,0,1] op_sel_hi:[0,0,1]
	v_fma_mix_f32 v66, v110, s80, v66 op_sel_hi:[0,0,1]
	v_pk_mul_f32 v[112:113], v[100:101], v[100:101]
	v_pk_mul_f32 v[114:115], v[68:69], v[68:69]
	v_pk_mul_f32 v[116:117], v[102:103], v[102:103]
	v_pk_mul_f32 v[118:119], v[66:67], v[66:67]
	v_add_f32_e32 v116, v116, v117
	v_add_f32_e32 v111, v118, v119
	v_add_f32_e32 v114, v114, v115
	v_add_f32_e32 v112, v112, v113
	v_add_f32_e32 v111, v111, v116
	v_add_f32_e32 v112, v114, v112
	v_add_f32_e32 v111, v111, v112
	v_add_f32_e32 v98, v98, v111
	ds_bpermute_b32 v111, v104, v98
	s_waitcnt lgkmcnt(0)
	v_add_f32_e32 v98, v98, v111
	ds_bpermute_b32 v111, v105, v98
	s_waitcnt lgkmcnt(0)
	v_add_f32_e32 v98, v98, v111
	ds_bpermute_b32 v111, v106, v98
	s_waitcnt lgkmcnt(0)
	v_add_f32_e32 v98, v98, v111
	ds_bpermute_b32 v111, v107, v98
	s_waitcnt lgkmcnt(0)
	v_add_f32_e32 v98, v98, v111
	ds_bpermute_b32 v111, v108, v98
	s_waitcnt lgkmcnt(0)
	v_add_f32_e32 v98, v98, v111
	ds_bpermute_b32 v111, v109, v98
	s_waitcnt lgkmcnt(0)
	v_add_f32_e32 v98, v98, v111
	v_fmamk_f32 v98, v98, 0x3a000000, v1
	v_cmp_gt_f32_e32 vcc, s81, v98
	v_mul_f32_e32 v111, 0x4f800000, v98
	s_nop 0
	v_cndmask_b32_e32 v98, v98, v111, vcc
	v_sqrt_f32_e32 v111, v98
	s_nop 0
	v_add_u32_e32 v112, -1, v111
	v_fma_f32 v113, -v112, v111, v98
	v_cmp_ge_f32_e64 s[4:5], 0, v113
	v_add_u32_e32 v113, 1, v111
	s_nop 0
	v_cndmask_b32_e64 v112, v111, v112, s[4:5]
	v_fma_f32 v111, -v113, v111, v98
	v_cmp_lt_f32_e64 s[4:5], 0, v111
	s_nop 1
	v_cndmask_b32_e64 v111, v112, v113, s[4:5]
	v_mul_f32_e32 v112, 0x37800000, v111
	v_cndmask_b32_e32 v111, v111, v112, vcc
	v_cmp_class_f32_e32 vcc, v98, v214
	s_nop 1
	v_cndmask_b32_e32 v98, v111, v98, vcc
	v_div_scale_f32 v111, s[4:5], v98, v98, 1.0
	v_rcp_f32_e32 v112, v111
	s_nop 0
	v_fma_f32 v113, -v111, v112, 1.0
	v_fmac_f32_e32 v112, v113, v112
	v_div_scale_f32 v113, vcc, 1.0, v98, 1.0
	v_mul_f32_e32 v114, v113, v112
	v_fma_f32 v115, -v111, v114, v113
	v_fmac_f32_e32 v114, v115, v112
	v_fma_f32 v111, -v111, v114, v113
	v_div_fmas_f32 v111, v111, v112, v114
	v_div_fixup_f32 v98, v111, v98, 1.0
	s_and_saveexec_b64 s[4:5], s[0:1]
	s_cbranch_execz .LBB0_188
	s_lshl_b64 s[18:19], s[12:13], 3
	s_add_u32 s18, s66, s18
	v_mul_f32_e32 v110, 0x3a000000, v110
	s_addc_u32 s19, s67, s19
	v_mov_b32_e32 v111, v98
	global_store_dwordx2 v99, v[110:111], s[18:19]
	s_branch .LBB0_188

; __device__ __forceinline__ float wave_sum(float v) {
; #pragma unroll
;     for (int o = 1; o < 64; o <<= 1) v += __shfl_xor(v, o);
;     return v;
.LBB0_905:
	s_cmp_lt_i32 s8, 1
	s_cbranch_scc1 .LBB0_912
	v_and_b32_e32 v67, 64, v217
	v_add_u32_e32 v67, 64, v67
	v_xor_b32_e32 v68, 1, v217
	v_cmp_lt_i32_e32 vcc, v68, v67
	v_readlane_b32 s4, v253, 34
	v_lshlrev_b32_e32 v98, 4, v66
	v_cndmask_b32_e32 v68, v217, v68, vcc
	v_lshlrev_b32_e32 v104, 2, v68
	v_xor_b32_e32 v68, 2, v217
	v_cmp_lt_i32_e32 vcc, v68, v67
	v_readlane_b32 s5, v253, 35
	v_lshl_add_u64 v[82:83], s[88:89], 0, v[98:99]
	v_cndmask_b32_e32 v68, v217, v68, vcc
	v_lshlrev_b32_e32 v105, 2, v68
	v_xor_b32_e32 v68, 4, v217
	v_cmp_lt_i32_e32 vcc, v68, v67
	s_mov_b32 s9, 0
	v_cmp_eq_u32_e64 s[0:1], 0, v66
	v_cndmask_b32_e32 v68, v217, v68, vcc
	v_lshlrev_b32_e32 v106, 2, v68
	v_xor_b32_e32 v68, 8, v217
	v_cmp_lt_i32_e32 vcc, v68, v67
	v_lshl_add_u64 v[84:85], s[4:5], 0, v[98:99]
	s_mov_b32 s12, s8
	v_cndmask_b32_e32 v68, v217, v68, vcc
	v_lshlrev_b32_e32 v107, 2, v68
	v_xor_b32_e32 v68, 16, v217
	v_cmp_lt_i32_e32 vcc, v68, v67
	v_readlane_b32 s13, v249, 41
	s_nop 0
	v_cndmask_b32_e32 v68, v217, v68, vcc
	v_lshlrev_b32_e32 v108, 2, v68
	v_xor_b32_e32 v68, 32, v217
	v_cmp_lt_i32_e32 vcc, v68, v67
	s_nop 1
	v_cndmask_b32_e32 v67, v217, v68, vcc
	v_lshlrev_b32_e32 v109, 2, v67
	s_not_b32 s100, s9
	s_add_i32 s100, s8, s100
	s_mul_i32 s100, s100, s64
	s_add_i32 s100, s100, s79
	s_and_b64 vcc, exec, s[2:3]
	s_cselect_b32 s100, s100, s13
	s_ashr_i32 s101, s100, 31
	s_lshl_b64 s[100:101], s[100:101], 12
	v_lshl_add_u64 v[170:171], v[82:83], 0, s[100:101]
	global_load_dwordx4 v[154:157], v[170:171], off
	global_load_dwordx4 v[158:161], v[170:171], off offset:1024
	global_load_dwordx4 v[162:165], v[170:171], off offset:2048
	global_load_dwordx4 v[166:169], v[170:171], off offset:3072
	s_branch .LBB0_908

.LBB0_910:
	s_ashr_i32 s7, s6, 31
	s_lshl_b64 s[4:5], s[6:7], 12
	v_lshl_add_u64 v[66:67], v[82:83], 0, s[4:5]
	s_sub_i32 s100, s6, s64
	s_add_i32 s101, s13, s43
	s_and_b64 vcc, exec, s[2:3]
	s_cselect_b32 s100, s100, s101
	s_ashr_i32 s101, s100, 31
	s_lshl_b64 s[100:101], s[100:101], 12
	v_lshl_add_u64 v[170:171], v[82:83], 0, s[100:101]
	s_cmp_lg_u32 s9, 0
	s_cbranch_scc1 .Lln_wB
	s_waitcnt vmcnt(0)
.Lln_wB:
	v_mov_b32_e32 v102, v99
	s_waitcnt vmcnt(8)
	v_mov_b64_e32 v[78:79], v[154:155]
	v_mov_b64_e32 v[80:81], v[156:157]
	v_cvt_f32_f16_sdwa v73, v80 dst_sel:DWORD dst_unused:UNUSED_PAD src0_sel:WORD_1
	v_cvt_f32_f16_sdwa v72, v78 dst_sel:DWORD dst_unused:UNUSED_PAD src0_sel:WORD_1
	v_cvt_f32_f16_e32 v75, v80
	v_cvt_f32_f16_e32 v74, v78
	v_cvt_f32_f16_sdwa v69, v81 dst_sel:DWORD dst_unused:UNUSED_PAD src0_sel:WORD_1
	v_cvt_f32_f16_sdwa v68, v79 dst_sel:DWORD dst_unused:UNUSED_PAD src0_sel:WORD_1
	v_cvt_f32_f16_e32 v71, v81
	v_pk_add_f32 v[72:73], v[74:75], v[72:73]
	v_cvt_f32_f16_e32 v70, v79
	v_pk_add_f32 v[68:69], v[70:71], v[68:69]
	s_nop 0
	v_pk_add_f32 v[68:69], v[72:73], v[68:69]
	s_waitcnt vmcnt(7)
	v_mov_b64_e32 v[74:75], v[158:159]
	v_mov_b64_e32 v[76:77], v[160:161]
	v_cvt_f32_f16_e32 v72, v74
	v_cvt_f32_f16_sdwa v73, v75 dst_sel:DWORD dst_unused:UNUSED_PAD src0_sel:WORD_1
	v_cvt_f32_f16_e32 v87, v75
	v_cvt_f32_f16_sdwa v86, v74 dst_sel:DWORD dst_unused:UNUSED_PAD src0_sel:WORD_1
	v_pk_add_f32 v[94:95], v[68:69], v[68:69] op_sel:[0,1] op_sel_hi:[1,0]
	v_cvt_f32_f16_e32 v68, v76
	v_cvt_f32_f16_sdwa v69, v77 dst_sel:DWORD dst_unused:UNUSED_PAD src0_sel:WORD_1
	v_cvt_f32_f16_e32 v71, v77
	v_cvt_f32_f16_sdwa v70, v76 dst_sel:DWORD dst_unused:UNUSED_PAD src0_sel:WORD_1
	v_pk_add_f32 v[72:73], v[86:87], v[72:73]
	v_pk_add_f32 v[68:69], v[70:71], v[68:69]
	v_pk_add_f32 v[96:97], v[72:73], v[72:73] op_sel:[0,1] op_sel_hi:[1,0]
	v_pk_add_f32 v[100:101], v[68:69], v[68:69] op_sel:[0,1] op_sel_hi:[1,0]
	s_waitcnt vmcnt(6)
	v_mov_b64_e32 v[70:71], v[162:163]
	v_mov_b64_e32 v[72:73], v[164:165]
	v_cvt_f32_f16_e32 v68, v73
	v_cvt_f32_f16_sdwa v69, v73 dst_sel:DWORD dst_unused:UNUSED_PAD src0_sel:WORD_1
	v_cvt_f32_f16_e32 v88, v71
	v_cvt_f32_f16_sdwa v89, v71 dst_sel:DWORD dst_unused:UNUSED_PAD src0_sel:WORD_1
	v_cvt_f32_f16_e32 v86, v72
	v_cvt_f32_f16_sdwa v87, v72 dst_sel:DWORD dst_unused:UNUSED_PAD src0_sel:WORD_1
	v_cvt_f32_f16_e32 v90, v70
	v_add_f32_e32 v92, v88, v89
	v_add_f32_e32 v88, v68, v69
	v_cvt_f32_f16_sdwa v91, v70 dst_sel:DWORD dst_unused:UNUSED_PAD src0_sel:WORD_1
	v_add_f32_e32 v86, v86, v87
	v_add_f32_e32 v90, v90, v91
	s_waitcnt vmcnt(5)
	v_mov_b64_e32 v[66:67], v[166:167]
	v_mov_b64_e32 v[68:69], v[168:169]
	s_cmp_eq_u32 s12, 1
	s_cbranch_scc1 .Lln_npB
	global_load_dwordx4 v[154:157], v[170:171], off
	global_load_dwordx4 v[158:161], v[170:171], off offset:1024
	global_load_dwordx4 v[162:165], v[170:171], off offset:2048
	global_load_dwordx4 v[166:169], v[170:171], off offset:3072
.Lln_npB:
	v_cvt_f32_f16_sdwa v89, v69 dst_sel:DWORD dst_unused:UNUSED_PAD src0_sel:WORD_1
	v_cvt_f32_f16_e32 v87, v69
	v_cvt_f32_f16_sdwa v93, v68 dst_sel:DWORD dst_unused:UNUSED_PAD src0_sel:WORD_1
	v_cvt_f32_f16_e32 v91, v68
	v_cvt_f32_f16_e32 v97, v67
	v_cvt_f32_f16_sdwa v101, v67 dst_sel:DWORD dst_unused:UNUSED_PAD src0_sel:WORD_1
	v_cvt_f32_f16_e32 v95, v66
	v_cvt_f32_f16_sdwa v103, v66 dst_sel:DWORD dst_unused:UNUSED_PAD src0_sel:WORD_1
	v_pk_add_f32 v[90:91], v[90:91], v[92:93]
	v_pk_add_f32 v[96:97], v[96:97], v[100:101]
	v_pk_add_f32 v[86:87], v[86:87], v[88:89]
	v_pk_add_f32 v[94:95], v[94:95], v[102:103]
	v_pk_add_f32 v[86:87], v[90:91], v[86:87]
	v_pk_add_f32 v[94:95], v[94:95], v[96:97]
	s_nop 0
	v_pk_add_f32 v[86:87], v[94:95], v[86:87]
	s_nop 0
	v_add_f32_e32 v86, v86, v87
	ds_bpermute_b32 v87, v104, v86
	s_waitcnt lgkmcnt(0)
	v_add_f32_e32 v86, v86, v87
	ds_bpermute_b32 v87, v105, v86
	s_waitcnt lgkmcnt(0)
	v_add_f32_e32 v86, v86, v87
	ds_bpermute_b32 v87, v106, v86
	s_waitcnt lgkmcnt(0)
	v_add_f32_e32 v86, v86, v87
	ds_bpermute_b32 v87, v107, v86
	s_waitcnt lgkmcnt(0)
	v_add_f32_e32 v86, v86, v87
	ds_bpermute_b32 v87, v108, v86
	s_waitcnt lgkmcnt(0)
	v_add_f32_e32 v86, v86, v87
	ds_bpermute_b32 v87, v109, v86
	s_waitcnt lgkmcnt(0)
	v_add_f32_e32 v110, v86, v87
	v_fma_mix_f32 v87, v110, s80, v81 op_sel:[0,0,1] op_sel_hi:[0,0,1]
	v_fma_mix_f32 v86, v110, s80, v81 op_sel_hi:[0,0,1]
	v_fma_mix_f32 v81, v110, s80, v80 op_sel:[0,0,1] op_sel_hi:[0,0,1]
	v_fma_mix_f32 v80, v110, s80, v80 op_sel_hi:[0,0,1]
	v_fma_mix_f32 v89, v110, s80, v79 op_sel:[0,0,1] op_sel_hi:[0,0,1]
	v_fma_mix_f32 v88, v110, s80, v79 op_sel_hi:[0,0,1]
	v_fma_mix_f32 v79, v110, s80, v78 op_sel:[0,0,1] op_sel_hi:[0,0,1]
	v_fma_mix_f32 v78, v110, s80, v78 op_sel_hi:[0,0,1]
	v_pk_mul_f32 v[90:91], v[86:87], v[86:87]
	v_pk_mul_f32 v[92:93], v[80:81], v[80:81]
	v_pk_mul_f32 v[94:95], v[88:89], v[88:89]
	v_pk_mul_f32 v[96:97], v[78:79], v[78:79]
	v_add_f32_e32 v94, v94, v95
	v_add_f32_e32 v96, v96, v97
	v_add_f32_e32 v92, v92, v93
	v_add_f32_e32 v90, v90, v91
	v_add_f32_e32 v94, v96, v94
	v_add_f32_e32 v90, v92, v90
	v_add_f32_e32 v98, v94, v90
	v_fma_mix_f32 v91, v110, s80, v77 op_sel:[0,0,1] op_sel_hi:[0,0,1]
	v_fma_mix_f32 v90, v110, s80, v77 op_sel_hi:[0,0,1]
	v_fma_mix_f32 v77, v110, s80, v76 op_sel:[0,0,1] op_sel_hi:[0,0,1]
	v_fma_mix_f32 v76, v110, s80, v76 op_sel_hi:[0,0,1]
	v_fma_mix_f32 v93, v110, s80, v75 op_sel:[0,0,1] op_sel_hi:[0,0,1]
	v_fma_mix_f32 v92, v110, s80, v75 op_sel_hi:[0,0,1]
	v_fma_mix_f32 v75, v110, s80, v74 op_sel:[0,0,1] op_sel_hi:[0,0,1]
	v_fma_mix_f32 v74, v110, s80, v74 op_sel_hi:[0,0,1]
	v_pk_mul_f32 v[94:95], v[90:91], v[90:91]
	v_pk_mul_f32 v[96:97], v[76:77], v[76:77]
	v_pk_mul_f32 v[100:101], v[92:93], v[92:93]
	v_pk_mul_f32 v[102:103], v[74:75], v[74:75]
	v_add_f32_e32 v100, v100, v101
	v_add_f32_e32 v102, v102, v103
	v_add_f32_e32 v96, v96, v97
	v_add_f32_e32 v94, v94, v95
	v_add_f32_e32 v100, v102, v100
	v_add_f32_e32 v94, v96, v94
	v_add_f32_e32 v94, v100, v94
	v_add_f32_e32 v98, v98, v94
	v_fma_mix_f32 v95, v110, s80, v73 op_sel:[0,0,1] op_sel_hi:[0,0,1]
	v_fma_mix_f32 v94, v110, s80, v73 op_sel_hi:[0,0,1]
	v_fma_mix_f32 v73, v110, s80, v72 op_sel:[0,0,1] op_sel_hi:[0,0,1]
	v_fma_mix_f32 v72, v110, s80, v72 op_sel_hi:[0,0,1]
	v_fma_mix_f32 v97, v110, s80, v71 op_sel:[0,0,1] op_sel_hi:[0,0,1]
	v_fma_mix_f32 v96, v110, s80, v71 op_sel_hi:[0,0,1]
	v_fma_mix_f32 v71, v110, s80, v70 op_sel:[0,0,1] op_sel_hi:[0,0,1]
	v_fma_mix_f32 v70, v110, s80, v70 op_sel_hi:[0,0,1]
	v_pk_mul_f32 v[100:101], v[94:95], v[94:95]
	v_pk_mul_f32 v[102:103], v[72:73], v[72:73]
	v_pk_mul_f32 v[112:113], v[96:97], v[96:97]
	v_pk_mul_f32 v[114:115], v[70:71], v[70:71]
	v_add_f32_e32 v112, v112, v113
	v_add_f32_e32 v111, v114, v115
	v_add_f32_e32 v102, v102, v103
	v_add_f32_e32 v100, v100, v101
	v_add_f32_e32 v111, v111, v112
	v_add_f32_e32 v100, v102, v100
	v_add_f32_e32 v100, v111, v100
	v_add_f32_e32 v98, v98, v100
	v_fma_mix_f32 v101, v110, s80, v69 op_sel:[0,0,1] op_sel_hi:[0,0,1]
	v_fma_mix_f32 v100, v110, s80, v69 op_sel_hi:[0,0,1]
	v_fma_mix_f32 v69, v110, s80, v68 op_sel:[0,0,1] op_sel_hi:[0,0,1]
	v_fma_mix_f32 v68, v110, s80, v68 op_sel_hi:[0,0,1]
	v_fma_mix_f32 v103, v110, s80, v67 op_sel:[0,0,1] op_sel_hi:[0,0,1]
	v_fma_mix_f32 v102, v110, s80, v67 op_sel_hi:[0,0,1]
	v_fma_mix_f32 v67, v110, s80, v66 op_sel:[0,0,1] op_sel_hi:[0,0,1]
	v_fma_mix_f32 v66, v110, s80, v66 op_sel_hi:[0,0,1]
	v_pk_mul_f32 v[112:113], v[100:101], v[100:101]
	v_pk_mul_f32 v[114:115], v[68:69], v[68:69]
	v_pk_mul_f32 v[116:117], v[102:103], v[102:103]
	v_pk_mul_f32 v[118:119], v[66:67], v[66:67]
	v_add_f32_e32 v116, v116, v117
	v_add_f32_e32 v111, v118, v119
	v_add_f32_e32 v114, v114, v115
	v_add_f32_e32 v112, v112, v113
	v_add_f32_e32 v111, v111, v116
	v_add_f32_e32 v112, v114, v112
	v_add_f32_e32 v111, v111, v112
	v_add_f32_e32 v98, v98, v111
	ds_bpermute_b32 v111, v104, v98
	s_waitcnt lgkmcnt(0)
	v_add_f32_e32 v98, v98, v111
	ds_bpermute_b32 v111, v105, v98
	s_waitcnt lgkmcnt(0)
	v_add_f32_e32 v98, v98, v111
	ds_bpermute_b32 v111, v106, v98
	s_waitcnt lgkmcnt(0)
	v_add_f32_e32 v98, v98, v111
	ds_bpermute_b32 v111, v107, v98
	s_waitcnt lgkmcnt(0)
	v_add_f32_e32 v98, v98, v111
	ds_bpermute_b32 v111, v108, v98
	s_waitcnt lgkmcnt(0)
	v_add_f32_e32 v98, v98, v111
	ds_bpermute_b32 v111, v109, v98
	s_waitcnt lgkmcnt(0)
	v_add_f32_e32 v98, v98, v111
	v_fmamk_f32 v98, v98, 0x3a000000, v1
	v_cmp_gt_f32_e32 vcc, s81, v98
	v_mul_f32_e32 v111, 0x4f800000, v98
	s_nop 0
	v_cndmask_b32_e32 v98, v98, v111, vcc
	v_sqrt_f32_e32 v111, v98
	s_nop 0
	v_add_u32_e32 v112, -1, v111
	v_fma_f32 v113, -v112, v111, v98
	v_cmp_ge_f32_e64 s[4:5], 0, v113
	v_add_u32_e32 v113, 1, v111
	s_nop 0
	v_cndmask_b32_e64 v112, v111, v112, s[4:5]
	v_fma_f32 v111, -v113, v111, v98
	v_cmp_lt_f32_e64 s[4:5], 0, v111
	s_nop 1
	v_cndmask_b32_e64 v111, v112, v113, s[4:5]
	v_mul_f32_e32 v112, 0x37800000, v111
	v_cndmask_b32_e32 v111, v111, v112, vcc
	v_cmp_class_f32_e32 vcc, v98, v214
	s_nop 1
	v_cndmask_b32_e32 v98, v111, v98, vcc
	v_div_scale_f32 v111, s[4:5], v98, v98, 1.0
	v_rcp_f32_e32 v112, v111
	s_nop 0
	v_fma_f32 v113, -v111, v112, 1.0
	v_fmac_f32_e32 v112, v113, v112
	v_div_scale_f32 v113, vcc, 1.0, v98, 1.0
	v_mul_f32_e32 v114, v113, v112
	v_fma_f32 v115, -v111, v114, v113
	v_fmac_f32_e32 v114, v115, v112
	v_fma_f32 v111, -v111, v114, v113
	v_div_fmas_f32 v111, v111, v112, v114
	v_div_fixup_f32 v98, v111, v98, 1.0
	s_and_saveexec_b64 s[4:5], s[0:1]
	s_cbranch_execz .LBB0_907
	s_lshl_b64 s[14:15], s[6:7], 3
	s_add_u32 s14, s66, s14
	v_mul_f32_e32 v110, 0x3a000000, v110
	s_addc_u32 s15, s67, s15
	v_mov_b32_e32 v111, v98
	global_store_dwordx2 v99, v[110:111], s[14:15]
	s_branch .LBB0_907
